# attention next-tile K/V loads: scalar tile base + per-unit 32-bit per-thread offsets instead of 64-bit VALU address math each iteration
# speedup vs baseline: 1.0026x; 1.0026x over previous
; #define LAS __attribute__((address_space(3)))
; __device__ __forceinline__ void attn_phase(const Ctx& c, const Params& p, int o, int first, int cidx) {
;     ...
;         f32x16 o0 = {}, o1 = {}; float mrun = -INFINITY, lrun = 0.f;
;         const int ntile = 4 * (qblk + 1);
;         const bf16_t* kg = KH + (size_t)(b * T_) * 768 + h * 96; const bf16_t* vg = VT + (size_t)bh * 64 * T_;
;         u32x4 rk0, rk1 = {}, rv;
;         rk0 = *(const u32x4*)(kg + (size_t)k0row * 768 + 8 * k0ch); if (k1on) rk1 = *(const u32x4*)(kg + (size_t)k1row * 768 + 8 * k1ch); rv = *(const u32x4*)(vg + (size_t)vrow * T_ + 8 * vch);
;         *(LAS u32x4*)(sK + k0row * 104 + 8 * k0ch) = rk0; if (k1on) *(LAS u32x4*)(sK + k1row * 104 + 8 * k1ch) = rk1; *(LAS u32x4*)(sVt + vrow * 72 + 8 * vch) = rv;
;         __syncthreads();
;         for (int kt = 0; kt < ntile; ++kt) { const int kv0 = kt * 64; const int buf = kt & 1;
;             if (kt + 1 < ntile) { const int kn = kv0 + 64;
;                 rk0 = *(const u32x4*)(kg + (size_t)(kn + k0row) * 768 + 8 * k0ch); if (k1on) rk1 = *(const u32x4*)(kg + (size_t)(kn + k1row) * 768 + 8 * k1ch); rv = *(const u32x4*)(vg + (size_t)vrow * T_ + kn + 8 * vch); }
.LBB0_117:
	s_or_b64 exec, exec, s[18:19]
	s_lshl_b32 s11, s11, 20
	s_and_b32 s42, s11, 0x1f00000
	v_lshl_add_u64 v[118:119], v[114:115], 0, s[42:43]
	global_load_dwordx4 v[98:101], v[118:119], off
	s_waitcnt vmcnt(0) lgkmcnt(0)
	ds_write_b128 v126, v[90:93]
	s_and_saveexec_b64 s[18:19], s[6:7]
	ds_write_b128 v134, v[94:97]
	s_or_b64 exec, exec, s[18:19]
	v_mov_b32_e32 v14, v0
	v_mov_b32_e32 v15, v0
	v_mov_b32_e32 v1, v0
	v_mov_b32_e32 v2, v0
	v_mov_b32_e32 v3, v0
	v_mov_b32_e32 v4, v0
	v_mov_b32_e32 v5, v0
	v_mov_b32_e32 v6, v0
	v_mov_b32_e32 v7, v0
	v_mov_b32_e32 v8, v0
	v_mov_b32_e32 v9, v0
	v_mov_b32_e32 v10, v0
	v_mov_b32_e32 v11, v0
	v_mov_b32_e32 v12, v0
	v_mov_b32_e32 v13, v0
	v_mov_b64_e32 v[32:33], v[14:15]
	s_lshl_b32 s10, s10, 2
	s_mov_b32 s42, 0
	v_mov_b64_e32 v[30:31], v[12:13]
	v_mov_b64_e32 v[28:29], v[10:11]
	v_mov_b64_e32 v[26:27], v[8:9]
	v_mov_b64_e32 v[24:25], v[6:7]
	v_mov_b64_e32 v[22:23], v[4:5]
	v_mov_b64_e32 v[20:21], v[2:3]
	v_mov_b64_e32 v[18:19], v[0:1]
	v_mov_b64_e32 v[16:17], v[14:15]
	v_ashrrev_i32_e32 v117, 31, v116
	s_sub_i32 s27, 0x80, s10
	v_lshl_add_u64 v[120:121], v[106:107], 1, s[2:3]
	v_lshl_add_u64 v[122:123], v[110:111], 1, s[2:3]
	v_subrev_u32_e32 v190, s22, v120
	v_subrev_u32_e32 v191, s22, v122
	v_subrev_u32_e32 v192, s22, v118
	v_subrev_u32_e32 v193, 64, v133
	v_mul_u32_u24_e32 v193, 0x600, v193
	v_add_u32_e32 v190, v190, v193
	v_subrev_u32_e32 v193, 64, v132
	v_mul_u32_u24_e32 v193, 0x600, v193
	v_add_u32_e32 v191, v191, v193
	s_addk_i32 s29, 0x1f1f
	v_or_b32_e32 v135, s26, v124
	v_mov_b32_e32 v136, 0
	v_mov_b32_e32 v137, 0xff800000
	v_mov_b64_e32 v[14:15], v[12:13]
	v_mov_b64_e32 v[12:13], v[10:11]
	v_mov_b64_e32 v[10:11], v[8:9]
	v_mov_b64_e32 v[8:9], v[6:7]
	v_mov_b64_e32 v[6:7], v[4:5]
	v_mov_b64_e32 v[4:5], v[2:3]
	v_mov_b64_e32 v[2:3], v[0:1]
	s_mov_b32 s10, s42
	ds_write_b64 v251, v[98:99] offset:26624
	ds_write_b64 v252, v[100:101] offset:26624
	s_waitcnt lgkmcnt(0)
	s_barrier
	v_readlane_b32 s11, v255, 5
	s_cmp_ge_u32 s11, 4
	s_cbranch_scc1 .Lsb_loop
.LBB0_120:
	s_add_i32 s31, s10, 1
	s_cmp_lt_u32 s31, s27
	s_cselect_b64 s[2:3], -1, 0
	s_cmp_ge_u32 s31, s27
	s_cbranch_scc1 .LBB0_124
	s_add_i32 s34, s42, 64
	s_mul_i32 s34, s34, 0x600
	s_add_u32 s34, s22, s34
	s_addc_u32 s35, s23, 0
	s_waitcnt vmcnt(0)
	global_load_dwordx4 v[90:93], v190, s[34:35]
	s_and_saveexec_b64 s[18:19], s[6:7]
	global_load_dwordx4 v[94:97], v191, s[34:35]
	s_or_b64 exec, exec, s[18:19]
	s_lshl_b32 s18, s42, 1
	s_add_u32 s18, s22, s18
	s_addc_u32 s19, s23, 0
	global_load_dwordx4 v[98:101], v192, s[18:19] offset:128

; __device__ __forceinline__ void attn_phase(const Ctx& c, const Params& p, int o, int first, int cidx) {
;     ...
;         for (int kt = 0; kt < ntile; ++kt) { const int kv0 = kt * 64; const int buf = kt & 1;
;             if (kt + 1 < ntile) { const int kn = kv0 + 64;
;                 rk0 = *(const u32x4*)(kg + (size_t)(kn + k0row) * 768 + 8 * k0ch); if (k1on) rk1 = *(const u32x4*)(kg + (size_t)(kn + k1row) * 768 + 8 * k1ch); rv = *(const u32x4*)(vg + (size_t)vrow * T_ + kn + 8 * vch); }
.Lsb_loop:
	s_setprio 1
	s_add_i32 s31, s10, 1
	s_cmp_lt_u32 s31, s27
	s_cselect_b64 s[2:3], -1, 0
	s_cmp_ge_u32 s31, s27
	s_cbranch_scc1 .Lsb_124
	s_add_i32 s34, s42, 64
	s_mul_i32 s34, s34, 0x600
	s_add_u32 s34, s22, s34
	s_addc_u32 s35, s23, 0
	s_waitcnt vmcnt(0)
	global_load_dwordx4 v[90:93], v190, s[34:35]
	s_and_saveexec_b64 s[18:19], s[6:7]
	global_load_dwordx4 v[94:97], v191, s[34:35]
	s_or_b64 exec, exec, s[18:19]
	s_lshl_b32 s18, s42, 1
	s_add_u32 s18, s22, s18
	s_addc_u32 s19, s23, 0
	global_load_dwordx4 v[98:101], v192, s[18:19] offset:128
